# P7: ffn_post_g hoisted out of row loop, counted waits instead of per-store vmcnt(0) drains
# speedup vs baseline: 1.0445x; 1.0058x over previous
; __global__ void __launch_bounds__(NTHR, 2) hymba_fwd(Params P) {
;     ...
;         for (int t0 = gw; t0 < NB * SEQ; t0 += 2 * NGW) {
;             f32x4 f[2][4], hv[2][4];
; #pragma unroll
;             for (int u = 0; u < 2; ++u) { int tr = t0 + u * NGW; tr = tr < NB * SEQ ? tr : NB * SEQ - 1;
;                 const int b = tr / SEQ, s = tr - b * SEQ; const size_t t = (size_t)b * LL + NMETA + s;
; #pragma unroll
;                 for (int j = 0; j < 4; ++j) { const u32x2 fq2 = __builtin_nontemporal_load((const u32x2*)(FB + (size_t)tr * 1024) + lane + 64 * j);
;                     f[u][j] = (f32x4){bflo(fq2.x), bfhi(fq2.x), bflo(fq2.y), bfhi(fq2.y)}; const u32x2 hq = __builtin_nontemporal_load((const u32x2*)(H1 + t * 1024) + lane + 64 * j); hv[u][j] = (f32x4){bflo(hq.x), bfhi(hq.x), bflo(hq.y), bfhi(hq.y)}; } }
; #pragma unroll
;             for (int u = 0; u < 2; ++u) { const int tr = t0 + u * NGW; if (tr >= NB * SEQ) continue;
;                 float ss = 0.f;
; #pragma unroll
;                 for (int j = 0; j < 4; ++j) ss += (f[u][j].x * f[u][j].x + f[u][j].y * f[u][j].y) + (f[u][j].z * f[u][j].z + f[u][j].w * f[u][j].w);
;                 const float rs = 1.f / sqrtf(wave_sum(ss) * (1.f / 1024.f) + EPS);
;                 f32x4* orow = (f32x4*)(P.out + (size_t)tr * 1024);
; #pragma unroll
;                 for (int j = 0; j < 4; ++j) { const f32x4 gg = *((const f32x4*)P.ffn_post_g + lane + 64 * j); __builtin_nontemporal_store(hv[u][j] + f[u][j] * rs * gg, &orow[lane + 64 * j]); }
.LBB0_1090:
	s_or_b64 exec, exec, s[0:1]
	s_cmpk_gt_i32 s70, 0x7fff
	s_waitcnt lgkmcnt(0)
	s_barrier
	s_cbranch_scc1 .LBB0_1095
	v_mbcnt_hi_u32_b32 v8, -1, v180
	v_and_b32_e32 v9, 64, v8
	v_add_u32_e32 v9, 64, v9
	v_xor_b32_e32 v10, 1, v8
	v_cmp_lt_i32_e32 vcc, v10, v9
	v_ashrrev_i32_e32 v153, 31, v152
	v_lshlrev_b64 v[2:3], 3, v[152:153]
	v_cndmask_b32_e32 v10, v8, v10, vcc
	v_lshlrev_b32_e32 v24, 2, v10
	v_xor_b32_e32 v10, 2, v8
	v_cmp_lt_i32_e32 vcc, v10, v9
	v_lshl_add_u64 v[0:1], s[2:3], 0, v[2:3]
	v_readlane_b32 s0, v237, 0
	v_cndmask_b32_e32 v10, v8, v10, vcc
	v_lshlrev_b32_e32 v25, 2, v10
	v_xor_b32_e32 v10, 4, v8
	v_cmp_lt_i32_e32 vcc, v10, v9
	v_readlane_b32 s1, v237, 1
	v_readlane_b32 s2, v237, 2
	v_cndmask_b32_e32 v10, v8, v10, vcc
	v_lshlrev_b32_e32 v26, 2, v10
	v_xor_b32_e32 v10, 8, v8
	v_cmp_lt_i32_e32 vcc, v10, v9
	v_readlane_b32 s3, v237, 3
	v_readlane_b32 s0, v237, 8
	v_cndmask_b32_e32 v10, v8, v10, vcc
	v_lshlrev_b32_e32 v27, 2, v10
	v_xor_b32_e32 v10, 16, v8
	v_cmp_lt_i32_e32 vcc, v10, v9
	v_lshlrev_b64 v[6:7], 4, v[152:153]
	v_readlane_b32 s4, v237, 4
	v_cndmask_b32_e32 v10, v8, v10, vcc
	v_lshlrev_b32_e32 v28, 2, v10
	v_xor_b32_e32 v10, 32, v8
	v_cmp_lt_i32_e32 vcc, v10, v9
	v_readlane_b32 s5, v237, 5
	v_readlane_b32 s6, v237, 6
	v_readlane_b32 s7, v237, 7
	v_cndmask_b32_e32 v8, v8, v10, vcc
	v_readlane_b32 s2, v237, 10
	v_readlane_b32 s3, v237, 11
	v_lshl_add_u64 v[2:3], s[92:93], 0, v[2:3]
	v_lshl_add_u64 v[4:5], s[4:5], 0, v[6:7]
	v_lshlrev_b32_e32 v29, 2, v8
	v_lshl_add_u64 v[6:7], s[6:7], 0, v[6:7]
	s_lshl_b32 s8, s2, 4
	s_mov_b64 s[2:3], 0x8000
	s_mov_b32 s9, 0x8000
	v_mov_b32_e32 v30, 0x358637bd
	s_mov_b32 s10, 0xf800000
	v_mov_b32_e32 v31, 0x260
	v_readlane_b32 s1, v237, 9
	global_load_dwordx4 v[80:83], v[4:5], off
	global_load_dwordx4 v[84:87], v[4:5], off offset:1024
	global_load_dwordx4 v[88:91], v[4:5], off offset:2048
	global_load_dwordx4 v[92:95], v[4:5], off offset:3072
	s_waitcnt vmcnt(0)
	s_branch .LBB0_1093

; __global__ void __launch_bounds__(NTHR, 2) hymba_fwd(Params P) {
;     ...
;             for (int u = 0; u < 2; ++u) { int tr = t0 + u * NGW; tr = tr < NB * SEQ ? tr : NB * SEQ - 1;
;                 const int b = tr / SEQ, s = tr - b * SEQ; const size_t t = (size_t)b * LL + NMETA + s;
; #pragma unroll
;                 for (int j = 0; j < 4; ++j) { const u32x2 fq2 = __builtin_nontemporal_load((const u32x2*)(FB + (size_t)tr * 1024) + lane + 64 * j);
;                     f[u][j] = (f32x4){bflo(fq2.x), bfhi(fq2.x), bflo(fq2.y), bfhi(fq2.y)}; const u32x2 hq = __builtin_nontemporal_load((const u32x2*)(H1 + t * 1024) + lane + 64 * j); hv[u][j] = (f32x4){bflo(hq.x), bfhi(hq.x), bflo(hq.y), bfhi(hq.y)}; } }
; #pragma unroll
;             for (int u = 0; u < 2; ++u) { const int tr = t0 + u * NGW; if (tr >= NB * SEQ) continue;
;                 float ss = 0.f;
; #pragma unroll
;                 for (int j = 0; j < 4; ++j) ss += (f[u][j].x * f[u][j].x + f[u][j].y * f[u][j].y) + (f[u][j].z * f[u][j].z + f[u][j].w * f[u][j].w);
;                 const float rs = 1.f / sqrtf(wave_sum(ss) * (1.f / 1024.f) + EPS);
.LBB0_1093:
	s_add_i32 s4, s89, s70
	s_min_i32 s6, s4, 0x7fff
	s_ashr_i32 s7, s6, 31
	s_lshr_b32 s0, s7, 20
	s_add_i32 s0, s6, s0
	s_ashr_i32 s1, s0, 12
	s_and_b32 s0, s0, 0xfffff000
	s_sub_i32 s0, s6, s0
	s_mul_hi_i32 s5, s1, 0x1010
	s_mulk_i32 s1, 0x1010
	s_ashr_i32 s11, s0, 31
	s_add_u32 s0, s1, s0
	s_addc_u32 s1, s5, s11
	s_ashr_i32 s71, s70, 31
	s_lshr_b32 s5, s71, 20
	s_add_i32 s5, s70, s5
	s_ashr_i32 s11, s5, 12
	s_and_b32 s5, s5, 0xfffff000
	s_sub_i32 s5, s70, s5
	s_lshl_b64 s[0:1], s[0:1], 11
	s_lshl_b64 s[6:7], s[6:7], 11
	s_mul_hi_i32 s13, s11, 0x1010
	s_mulk_i32 s11, 0x1010
	s_ashr_i32 s14, s5, 31
	s_add_u32 s12, s11, s5
	s_addc_u32 s13, s13, s14
	s_lshl_b64 s[14:15], s[70:71], 11
	v_lshl_add_u64 v[8:9], v[0:1], 0, s[14:15]
	s_lshl_b64 s[12:13], s[12:13], 11
	global_load_dwordx2 v[10:11], v[8:9], off offset:1536 nt
	global_load_dwordx2 v[12:13], v[8:9], off nt
	global_load_dwordx2 v[16:17], v[8:9], off offset:512 nt
	v_lshl_add_u64 v[14:15], v[2:3], 0, s[12:13]
	v_add_co_u32_e32 v18, vcc, s9, v14
	v_lshl_add_u64 v[56:57], v[14:15], 0, s[2:3]
	s_nop 0
	v_addc_co_u32_e32 v19, vcc, 0, v15, vcc
	global_load_dwordx2 v[36:37], v[18:19], off nt
	global_load_dwordx2 v[20:21], v[8:9], off offset:1024 nt
	s_waitcnt vmcnt(4)
	v_lshlrev_b32_e32 v39, 16, v10
	s_waitcnt vmcnt(3)
	v_and_b32_e32 v45, 0xffff0000, v12
	v_and_b32_e32 v47, 0xffff0000, v13
	v_mov_b32_e32 v9, v39
	v_lshlrev_b32_e32 v44, 16, v12
	v_lshlrev_b32_e32 v46, 16, v13
	s_waitcnt vmcnt(2)
	v_and_b32_e32 v51, 0xffff0000, v17
	v_and_b32_e32 v50, 0xffff0000, v16
	v_mul_f32_e32 v8, v47, v47
	v_mul_f32_e32 v12, v45, v45
	v_and_b32_e32 v41, 0xffff0000, v10
	v_lshlrev_b32_e32 v42, 16, v11
	v_and_b32_e32 v43, 0xffff0000, v11
	v_lshlrev_b32_e32 v49, 16, v17
	v_lshlrev_b32_e32 v48, 16, v16
	s_waitcnt vmcnt(0)
	v_lshlrev_b32_e32 v52, 16, v20
	v_and_b32_e32 v53, 0xffff0000, v20
	v_lshlrev_b32_e32 v54, 16, v21
	v_and_b32_e32 v55, 0xffff0000, v21
	v_pk_mul_f32 v[10:11], v[50:51], v[50:51]
	v_pk_fma_f32 v[20:21], v[46:47], v[46:47], v[8:9] op_sel_hi:[1,1,0]
	v_pk_fma_f32 v[12:13], v[44:45], v[44:45], v[12:13] op_sel_hi:[1,1,0]
	v_mul_f32_e32 v16, v53, v53
	v_mul_f32_e32 v18, v55, v55
	v_pk_fma_f32 v[10:11], v[48:49], v[48:49], v[10:11]
	v_mov_b32_e32 v38, v12
	v_mov_b32_e32 v8, v20
	v_mul_f32_e32 v22, v41, v41
	v_mul_f32_e32 v23, v42, v42
	v_mul_f32_e32 v40, v43, v43
	v_pk_fma_f32 v[16:17], v[52:53], v[52:53], v[16:17] op_sel_hi:[1,1,0]
	v_pk_fma_f32 v[18:19], v[54:55], v[54:55], v[18:19] op_sel_hi:[1,1,0]
	v_pk_add_f32 v[12:13], v[12:13], v[20:21]
	v_pk_add_f32 v[10:11], v[10:11], v[10:11] op_sel:[0,1] op_sel_hi:[1,0]
	v_pk_mul_f32 v[8:9], v[38:39], v[8:9]
	v_mov_b32_e32 v17, v23
	v_mov_b32_e32 v19, v40
	v_mov_b32_e32 v11, v22
	v_mov_b32_e32 v13, v9
	v_pk_add_f32 v[16:17], v[16:17], v[18:19]
	v_pk_add_f32 v[8:9], v[12:13], v[10:11]
	v_lshl_add_u64 v[10:11], v[2:3], 0, s[0:1]
	v_pk_add_f32 v[8:9], v[8:9], v[16:17]
	v_add_co_u32_e32 v60, vcc, s9, v10
	v_add_f32_e32 v8, v8, v9
	ds_bpermute_b32 v9, v24, v8
	v_addc_co_u32_e32 v61, vcc, 0, v11, vcc
	v_lshl_add_u64 v[58:59], v[10:11], 0, s[2:3]
	s_lshl_b64 s[0:1], s[70:71], 12
	s_waitcnt lgkmcnt(0)
	v_add_f32_e32 v12, v8, v9
	ds_bpermute_b32 v13, v25, v12
	v_lshl_add_u64 v[8:9], v[0:1], 0, s[6:7]
	global_load_dwordx2 v[20:21], v[8:9], off nt
	global_load_dwordx2 v[18:19], v[8:9], off offset:512 nt
	global_load_dwordx2 v[16:17], v[8:9], off offset:1024 nt
	global_load_dwordx2 v[22:23], v[8:9], off offset:1536 nt
	s_cmpk_gt_i32 s4, 0x7fff
	s_waitcnt lgkmcnt(0)
	v_add_f32_e32 v12, v12, v13
	ds_bpermute_b32 v13, v26, v12
	s_waitcnt lgkmcnt(0)
	v_add_f32_e32 v8, v12, v13
	ds_bpermute_b32 v9, v27, v8
	s_waitcnt lgkmcnt(0)
	v_add_f32_e32 v38, v8, v9
	ds_bpermute_b32 v40, v28, v38
	global_load_dwordx2 v[14:15], v[60:61], off nt
	global_load_dwordx2 v[12:13], v[58:59], off offset:512 nt
	global_load_dwordx2 v[10:11], v[58:59], off offset:1024 nt
	global_load_dwordx2 v[8:9], v[58:59], off offset:1536 nt
	v_lshl_add_u64 v[58:59], v[6:7], 0, s[0:1]
	global_load_dwordx2 v[60:61], v[56:57], off offset:1536 nt
	global_load_dwordx2 v[62:63], v[56:57], off offset:1024 nt
	global_load_dwordx2 v[64:65], v[56:57], off offset:512 nt
	v_lshlrev_b32_e32 v56, 16, v36
	s_waitcnt lgkmcnt(0)
	v_add_f32_e32 v38, v38, v40
	ds_bpermute_b32 v40, v29, v38
	v_and_b32_e32 v57, 0xffff0000, v36
	v_lshlrev_b32_e32 v36, 16, v37
	v_and_b32_e32 v37, 0xffff0000, v37
	s_waitcnt lgkmcnt(0)
	v_add_f32_e32 v38, v38, v40
	v_fmamk_f32 v38, v38, 0x3a800000, v30
	v_mul_f32_e32 v40, 0x4f800000, v38
	v_cmp_gt_f32_e32 vcc, s10, v38
	s_nop 1
	v_cndmask_b32_e32 v38, v38, v40, vcc
	v_sqrt_f32_e32 v40, v38
	s_nop 0
	v_add_u32_e32 v66, -1, v40
	v_add_u32_e32 v67, 1, v40
	v_fma_f32 v68, -v66, v40, v38
	v_fma_f32 v69, -v67, v40, v38
	v_cmp_ge_f32_e64 s[0:1], 0, v68
	s_nop 1
	v_cndmask_b32_e64 v40, v40, v66, s[0:1]
	v_cmp_lt_f32_e64 s[0:1], 0, v69
	s_nop 1
	v_cndmask_b32_e64 v40, v40, v67, s[0:1]
	v_mul_f32_e32 v66, 0x37800000, v40
	v_cndmask_b32_e32 v40, v40, v66, vcc
	v_cmp_class_f32_e32 vcc, v38, v31
	s_nop 1
	v_cndmask_b32_e32 v38, v40, v38, vcc
	v_div_scale_f32 v40, s[0:1], v38, v38, 1.0
	v_rcp_f32_e32 v66, v40
	v_div_scale_f32 v67, vcc, 1.0, v38, 1.0
	v_fma_f32 v68, -v40, v66, 1.0
	v_fmac_f32_e32 v66, v68, v66
	v_mul_f32_e32 v68, v67, v66
	v_fma_f32 v69, -v40, v68, v67
	v_fmac_f32_e32 v68, v69, v66
	v_fma_f32 v40, -v40, v68, v67
	v_div_fmas_f32 v40, v40, v66, v68
	v_div_fixup_f32 v38, v40, v38, 1.0
	v_pk_mul_f32 v[44:45], v[38:39], v[44:45] op_sel_hi:[0,1]
	v_pk_mul_f32 v[46:47], v[38:39], v[46:47] op_sel_hi:[0,1]
	s_waitcnt vmcnt(11)
; __global__ void __launch_bounds__(NTHR, 2) hymba_fwd(Params P) {
;     ...
;             for (int u = 0; u < 2; ++u) { const int tr = t0 + u * NGW; if (tr >= NB * SEQ) continue;
;                 float ss = 0.f;
; #pragma unroll
;                 for (int j = 0; j < 4; ++j) ss += (f[u][j].x * f[u][j].x + f[u][j].y * f[u][j].y) + (f[u][j].z * f[u][j].z + f[u][j].w * f[u][j].w);
;                 const float rs = 1.f / sqrtf(wave_sum(ss) * (1.f / 1024.f) + EPS);
;                 f32x4* orow = (f32x4*)(P.out + (size_t)tr * 1024);
; #pragma unroll
;                 for (int j = 0; j < 4; ++j) { const f32x4 gg = *((const f32x4*)P.ffn_post_g + lane + 64 * j); __builtin_nontemporal_store(hv[u][j] + f[u][j] * rs * gg, &orow[lane + 64 * j]); }
	v_pk_fma_f32 v[34:35], v[82:83], v[46:47], v[36:37]
	v_pk_fma_f32 v[32:33], v[80:81], v[44:45], v[56:57]
	global_store_dwordx4 v[58:59], v[32:35], off nt
	s_nop 1
	v_mov_b32_e32 v46, v49
	v_mov_b32_e32 v47, v51
	v_mov_b32_e32 v49, v50
	v_pk_mul_f32 v[46:47], v[38:39], v[46:47] op_sel_hi:[0,1]
	v_pk_mul_f32 v[48:49], v[38:39], v[48:49] op_sel_hi:[0,1]
	v_mov_b32_e32 v40, v39
	v_pk_mul_f32 v[42:43], v[38:39], v[42:43] op_sel_hi:[0,1]
	s_waitcnt vmcnt(1)
	v_lshlrev_b32_e32 v36, 16, v64
	v_and_b32_e32 v37, 0xffff0000, v64
	v_lshlrev_b32_e32 v44, 16, v65
	v_and_b32_e32 v45, 0xffff0000, v65
	v_pk_fma_f32 v[32:33], v[84:85], v[48:49], v[36:37]
	v_pk_fma_f32 v[34:35], v[86:87], v[46:47], v[44:45]
	global_store_dwordx4 v[58:59], v[32:35], off offset:1024 nt
	s_nop 1
	v_lshlrev_b32_e32 v36, 16, v62
	v_and_b32_e32 v37, 0xffff0000, v62
	v_lshlrev_b32_e32 v44, 16, v63
	v_and_b32_e32 v45, 0xffff0000, v63
	v_pk_mul_f32 v[46:47], v[38:39], v[54:55] op_sel_hi:[0,1]
	v_pk_mul_f32 v[48:49], v[38:39], v[52:53] op_sel_hi:[0,1]
	v_pk_mul_f32 v[38:39], v[38:39], v[40:41] op_sel_hi:[0,1]
	v_pk_fma_f32 v[32:33], v[88:89], v[48:49], v[36:37]
	v_pk_fma_f32 v[34:35], v[90:91], v[46:47], v[44:45]
	global_store_dwordx4 v[58:59], v[32:35], off offset:2048 nt
	s_nop 1
	v_lshlrev_b32_e32 v36, 16, v60
	v_and_b32_e32 v37, 0xffff0000, v60
	v_lshlrev_b32_e32 v44, 16, v61
	v_and_b32_e32 v45, 0xffff0000, v61
	v_pk_fma_f32 v[32:33], v[92:93], v[38:39], v[36:37]
	v_pk_fma_f32 v[34:35], v[94:95], v[42:43], v[44:45]
	global_store_dwordx4 v[58:59], v[32:35], off offset:3072 nt
	s_nop 1
	s_cbranch_scc1 .LBB0_1092
	s_waitcnt vmcnt(4)
	v_lshlrev_b32_e32 v36, 16, v20
	v_and_b32_e32 v37, 0xffff0000, v20
	v_lshlrev_b32_e32 v20, 16, v21
	v_and_b32_e32 v21, 0xffff0000, v21
	v_lshlrev_b32_e32 v33, 16, v22
	v_mul_f32_e32 v32, v21, v21
	v_and_b32_e32 v43, 0xffff0000, v19
	v_and_b32_e32 v42, 0xffff0000, v18
	v_lshlrev_b32_e32 v44, 16, v16
	v_and_b32_e32 v45, 0xffff0000, v16
	v_mul_f32_e32 v16, v37, v37
	v_pk_fma_f32 v[38:39], v[20:21], v[20:21], v[32:33] op_sel_hi:[1,1,0]
	v_lshlrev_b32_e32 v41, 16, v19
	v_lshlrev_b32_e32 v40, 16, v18
	v_pk_mul_f32 v[18:19], v[42:43], v[42:43]
	v_lshlrev_b32_e32 v46, 16, v17
	v_and_b32_e32 v47, 0xffff0000, v17
	v_pk_fma_f32 v[16:17], v[36:37], v[36:37], v[16:17] op_sel_hi:[1,1,0]
	v_and_b32_e32 v35, 0xffff0000, v22
	v_pk_fma_f32 v[18:19], v[40:41], v[40:41], v[18:19]
	v_mov_b32_e32 v32, v16
	v_mov_b32_e32 v48, v38
	v_mov_b32_e32 v49, v33
	v_mul_f32_e32 v34, v35, v35
	v_pk_add_f32 v[16:17], v[16:17], v[38:39]
	v_pk_mul_f32 v[38:39], v[32:33], v[48:49]
	v_pk_add_f32 v[18:19], v[18:19], v[18:19] op_sel:[0,1] op_sel_hi:[1,0]
	v_mov_b32_e32 v17, v39
	v_mov_b32_e32 v19, v34
	v_lshlrev_b32_e32 v22, 16, v23
	v_and_b32_e32 v23, 0xffff0000, v23
	v_pk_add_f32 v[38:39], v[16:17], v[18:19]
	v_mul_f32_e32 v16, v45, v45
	v_mul_f32_e32 v18, v47, v47
	v_mul_f32_e32 v50, v22, v22
	v_mul_f32_e32 v51, v23, v23
	v_pk_fma_f32 v[16:17], v[44:45], v[44:45], v[16:17] op_sel_hi:[1,1,0]
	v_pk_fma_f32 v[18:19], v[46:47], v[46:47], v[18:19] op_sel_hi:[1,1,0]
	v_mov_b32_e32 v17, v50
	v_mov_b32_e32 v19, v51
	v_pk_add_f32 v[48:49], v[16:17], v[18:19]
	v_pk_add_f32 v[38:39], v[38:39], v[48:49]
	s_ashr_i32 s5, s4, 31
	v_add_f32_e32 v32, v38, v39
	ds_bpermute_b32 v34, v24, v32
	v_lshlrev_b32_e32 v38, 16, v14
	s_waitcnt lgkmcnt(0)
	v_add_f32_e32 v32, v32, v34
	ds_bpermute_b32 v34, v25, v32
	s_waitcnt lgkmcnt(0)
	v_add_f32_e32 v32, v32, v34
	ds_bpermute_b32 v34, v26, v32
	s_waitcnt lgkmcnt(0)
	v_add_f32_e32 v32, v32, v34
	ds_bpermute_b32 v34, v27, v32
	s_waitcnt lgkmcnt(0)
	v_add_f32_e32 v32, v32, v34
	ds_bpermute_b32 v34, v28, v32
	s_waitcnt lgkmcnt(0)
	v_add_f32_e32 v32, v32, v34
	ds_bpermute_b32 v34, v29, v32
	s_waitcnt lgkmcnt(0)
	v_add_f32_e32 v32, v32, v34
	v_fmamk_f32 v32, v32, 0x3a800000, v30
	v_mul_f32_e32 v34, 0x4f800000, v32
	v_cmp_gt_f32_e32 vcc, s10, v32
	s_nop 1
	v_cndmask_b32_e32 v32, v32, v34, vcc
	v_sqrt_f32_e32 v34, v32
	s_nop 0
	v_add_u32_e32 v39, -1, v34
	v_fma_f32 v48, -v39, v34, v32
	v_cmp_ge_f32_e64 s[0:1], 0, v48
	v_add_u32_e32 v48, 1, v34
	s_nop 0
	v_cndmask_b32_e64 v39, v34, v39, s[0:1]
	v_fma_f32 v34, -v48, v34, v32
	v_cmp_lt_f32_e64 s[0:1], 0, v34
	s_nop 1
	v_cndmask_b32_e64 v34, v39, v48, s[0:1]
	v_mul_f32_e32 v39, 0x37800000, v34
	v_cndmask_b32_e32 v34, v34, v39, vcc
	v_cmp_class_f32_e32 vcc, v32, v31
	v_and_b32_e32 v39, 0xffff0000, v14
	v_lshlrev_b32_e32 v14, 16, v15
	v_cndmask_b32_e32 v32, v34, v32, vcc
	v_div_scale_f32 v34, s[0:1], v32, v32, 1.0
	v_rcp_f32_e32 v48, v34
	v_and_b32_e32 v15, 0xffff0000, v15
	s_lshl_b64 s[0:1], s[4:5], 12
	v_fma_f32 v49, -v34, v48, 1.0
	v_fmac_f32_e32 v48, v49, v48
	v_div_scale_f32 v49, vcc, 1.0, v32, 1.0
	v_mul_f32_e32 v50, v49, v48
	v_fma_f32 v51, -v34, v50, v49
	v_fmac_f32_e32 v50, v51, v48
	v_fma_f32 v34, -v34, v50, v49
	v_div_fmas_f32 v34, v34, v48, v50
	v_div_fixup_f32 v32, v34, v32, 1.0
	v_pk_mul_f32 v[36:37], v[32:33], v[36:37] op_sel_hi:[0,1]
	v_pk_mul_f32 v[20:21], v[32:33], v[20:21] op_sel_hi:[0,1]
	v_pk_fma_f32 v[18:19], v[82:83], v[20:21], v[14:15]
	v_pk_fma_f32 v[16:17], v[80:81], v[36:37], v[38:39]
	v_lshl_add_u64 v[20:21], v[6:7], 0, s[0:1]
	global_store_dwordx4 v[20:21], v[16:19], off nt
	s_nop 1
	v_lshlrev_b32_e32 v36, 16, v13
	v_lshlrev_b32_e32 v18, 16, v12
	v_and_b32_e32 v19, 0xffff0000, v12
	v_and_b32_e32 v37, 0xffff0000, v13
	v_mov_b32_e32 v12, v41
	v_mov_b32_e32 v13, v43
	v_mov_b32_e32 v41, v42
	v_pk_mul_f32 v[38:39], v[32:33], v[12:13] op_sel_hi:[0,1]
	v_pk_mul_f32 v[12:13], v[32:33], v[40:41] op_sel_hi:[0,1]
	v_mov_b32_e32 v34, v33
	v_pk_fma_f32 v[12:13], v[84:85], v[12:13], v[18:19]
	v_pk_fma_f32 v[14:15], v[86:87], v[38:39], v[36:37]
	global_store_dwordx4 v[20:21], v[12:15], off offset:1024 nt
	s_nop 1
	v_lshlrev_b32_e32 v16, 16, v10
	v_and_b32_e32 v17, 0xffff0000, v10
	v_lshlrev_b32_e32 v18, 16, v11
	v_and_b32_e32 v19, 0xffff0000, v11
	v_pk_mul_f32 v[36:37], v[32:33], v[46:47] op_sel_hi:[0,1]
	v_pk_mul_f32 v[10:11], v[32:33], v[44:45] op_sel_hi:[0,1]
	v_pk_fma_f32 v[10:11], v[88:89], v[10:11], v[16:17]
	v_pk_fma_f32 v[12:13], v[90:91], v[36:37], v[18:19]
	global_store_dwordx4 v[20:21], v[10:13], off offset:2048 nt
	s_nop 1
	v_lshlrev_b32_e32 v14, 16, v8
	v_and_b32_e32 v15, 0xffff0000, v8
	v_lshlrev_b32_e32 v16, 16, v9
	v_and_b32_e32 v17, 0xffff0000, v9
	v_pk_mul_f32 v[18:19], v[32:33], v[22:23] op_sel_hi:[0,1]
	v_pk_mul_f32 v[8:9], v[32:33], v[34:35] op_sel_hi:[0,1]
	v_pk_fma_f32 v[8:9], v[92:93], v[8:9], v[14:15]
	v_pk_fma_f32 v[10:11], v[94:95], v[18:19], v[16:17]
	global_store_dwordx4 v[20:21], v[8:11], off offset:3072 nt
	s_nop 1
	s_branch .LBB0_1092
